# A/B of the static priority raise: waves 0-3 raised instead of waves 4-7 in NSA prompt units
# speedup vs baseline: 1.0110x; 1.0057x over previous
.LBB0_2269:
	v_mov_b32_e32 v138, v0
	s_cmp_lg_u32 s4, s37
	v_readfirstlane_b32 s84, v138
	s_mov_b64 s[6:7], -1
	s_cbranch_scc0 .LBB0_2283
	s_cmpk_ge_u32 s84, 0x100
	s_cbranch_scc1 .Lmy_p0_lo
	s_setprio 1

.LBB0_4876:
	v_mov_b32_e32 v138, v0
	s_cmp_eq_u32 s4, s74
	v_readfirstlane_b32 s86, v138
	s_mov_b64 s[6:7], -1
	s_cbranch_scc1 .LBB0_4890
	s_cmpk_ge_u32 s86, 0x100
	s_cbranch_scc1 .Lmy_p1_lo
	s_setprio 1
